# cooperative-groups grid sync at P0->P1 replaced: block 0 zeroes barrier words write-through + magic flag, all poll flag, then xcd barrier (loop-bottom instance entered with layer=-1)
# speedup vs baseline: 1.0451x; 1.0451x over previous
.LBB0_6:
	v_add_u32_e32 v6, -2, v6
	v_ashrrev_i32_e32 v9, 31, v3
	v_mov_b32_e32 v8, v3
	v_ashrrev_i32_e32 v11, 31, v2
	v_mov_b32_e32 v10, v2
	v_cmp_eq_u32_e32 vcc, 0, v6
	v_add_u32_e32 v3, 0x400, v3
	v_add_u32_e32 v2, 0x400, v2
	v_lshl_add_u64 v[10:11], v[10:11], 2, s[30:31]
	v_lshl_add_u64 v[8:9], v[8:9], 2, s[30:31]
	s_or_b64 s[12:13], vcc, s[12:13]
	global_store_dword v[10:11], v5, off sc1
	global_store_dword v[8:9], v5, off sc1
	s_andn2_b64 exec, exec, s[12:13]
	s_cbranch_execnz .LBB0_6
	s_or_b64 exec, exec, s[12:13]
	v_cmp_ne_u32_e32 vcc, v1, v4
	v_lshl_add_u32 v2, v4, 9, v34
	s_orn2_b64 s[12:13], vcc, exec

.LBB0_10:
	v_add_u32_e32 v1, 0x200, v1
	v_cmp_lt_i32_e32 vcc, s14, v1
	global_store_dword v[2:3], v4, off sc1
	s_or_b64 s[4:5], vcc, s[4:5]
	v_lshl_add_u64 v[2:3], v[2:3], 0, s[12:13]
	s_andn2_b64 exec, exec, s[4:5]
	s_cbranch_execnz .LBB0_10
.LBB0_11:
	s_or_b64 exec, exec, s[0:1]
	v_readlane_b32 s0, v252, 0
	s_cmp_lg_u32 s0, 0
	s_cbranch_scc1 .Lflag_skip
	s_waitcnt vmcnt(0)
	s_barrier
	v_cmp_eq_u32_e32 vcc, 0, v34
	s_and_saveexec_b64 s[4:5], vcc
	s_cbranch_execz .Lflag_w
	s_add_u32 s12, s30, 0xc000
	s_addc_u32 s13, s31, 0
	v_mov_b32_e32 v2, 0x600df1a6
	v_mov_b32_e32 v3, 0
	global_store_dword v3, v2, s[12:13] sc1
	s_waitcnt vmcnt(0)

.Lflag_skip:
	s_nop 1
	v_lshl_add_u32 v2, s0, 9, v34
	s_movk_i32 s0, 0x6000
	v_cmp_gt_i32_e32 vcc, s0, v2
	s_and_saveexec_b64 s[0:1], vcc
	s_cbranch_execz .LBB0_14
	s_lshl_b32 s4, s3, 9
	v_ashrrev_i32_e32 v3, 31, v2
	v_lshl_add_u64 v[4:5], v[2:3], 3, s[30:31]
	s_mov_b64 s[12:13], 0x110000
	s_ashr_i32 s5, s4, 31
	v_mov_b32_e32 v6, 0
	v_lshl_add_u64 v[4:5], v[4:5], 0, s[12:13]
	s_lshl_b64 s[12:13], s[4:5], 3
	s_mov_b64 s[14:15], 0
	v_mov_b32_e32 v7, v6
	s_movk_i32 s5, 0x5fff

.LBB0_96:
	v_readlane_b32 s0, v252, 9
	v_readlane_b32 s1, v252, 10
	s_cmp_gt_u32 s1, 1
	s_cselect_b64 s[0:1], -1, 0
	s_and_b64 s[0:1], s[10:11], s[0:1]
	s_andn2_b64 vcc, exec, s[0:1]
	s_cbranch_vccnz .LBB0_108
	v_cmp_eq_u32_e32 vcc, 0, v194
	s_and_saveexec_b64 s[0:1], vcc
	s_cbranch_execz .LBB0_107
	s_add_u32 s4, s30, 0xc000
	s_addc_u32 s5, s31, 0
	s_mov_b32 s2, 0x600df1a6
	v_mov_b32_e32 v0, 0
.Lflag_poll:
	global_load_dword v2, v0, s[4:5] sc1
	s_waitcnt vmcnt(0)
	v_cmp_eq_u32_e32 vcc, s2, v2
	s_nop 1
	s_cbranch_vccnz .LBB0_107
	s_sleep 1
	s_branch .Lflag_poll
.LBB0_107:
	s_or_b64 exec, exec, s[0:1]
.LBB0_108:
	s_add_u32 s4, s30, 0x4000
	s_getreg_b32 s0, hwreg(HW_REG_XCC_ID, 0, 4)
	s_addc_u32 s5, s31, 0
	s_and_b32 s2, s0, 15
	s_mov_b32 s15, 0
	s_lshl_b32 s10, s2, 6
	v_cmp_eq_u32_e64 s[8:9], 0, v194
	s_mov_b64 s[0:1], exec
	s_nop 0
	v_writelane_b32 v252, s8, 31
	s_nop 1
	v_writelane_b32 v252, s9, 32
	s_and_b64 s[8:9], s[0:1], s[8:9]
	s_mov_b64 exec, s[8:9]
	s_cbranch_execz .LBB0_111
	s_mov_b64 s[8:9], exec
	v_mbcnt_lo_u32_b32 v0, s8, 0
	v_mbcnt_hi_u32_b32 v0, s9, v0
	v_cmp_eq_u32_e32 vcc, 0, v0
	s_and_b64 s[12:13], exec, vcc
	s_mov_b64 exec, s[12:13]
	s_cbranch_execz .LBB0_111
	s_lshl_b32 s11, s10, 2
	s_bcnt1_i32_b64 s8, s[8:9]
	v_mov_b32_e32 v0, s11
	v_mov_b32_e32 v1, s8
	global_atomic_add v0, v1, s[4:5] offset:1024
.LBB0_111:
	s_or_b64 exec, exec, s[0:1]
	s_add_u32 s0, s30, 0x100000
	v_writelane_b32 v252, s0, 33
	s_addc_u32 s0, s31, 0
	s_add_u32 s16, s30, 0x9a00000
	s_addc_u32 s17, s31, 0
	v_writelane_b32 v252, s0, 34
	s_add_u32 s0, s30, 0xba00000
	s_addc_u32 s1, s31, 0
	s_add_u32 s8, s30, 0x12e00000
	s_addc_u32 s9, s31, 0
	s_add_u32 s12, s30, 0x13000000
	v_writelane_b32 v252, s8, 35
	s_addc_u32 s13, s31, 0
	v_mov_b32_e32 v1, 0
	v_writelane_b32 v252, s9, 36
	s_add_u32 s8, s30, 0x15000000
	s_addc_u32 s9, s31, 0
	v_writelane_b32 v252, s8, 37
	v_mbcnt_lo_u32_b32 v0, -1, 0
	v_mov_b32_e32 v195, 0x358637bd
	v_writelane_b32 v252, s9, 38
	s_add_u32 s8, s30, 0x17400000
	s_addc_u32 s9, s31, 0
	v_writelane_b32 v252, s8, 39
	v_mov_b32_e32 v197, 0x3ecc95a3
	v_mbcnt_hi_u32_b32 v198, -1, v0
	v_writelane_b32 v252, s9, 40
	s_add_u32 s8, s30, 0x17600000
	s_addc_u32 s9, s31, 0
	v_writelane_b32 v252, s8, 41
	v_mov_b32_e32 v177, 1.0
	v_mov_b32_e32 v199, 0x7f800000
	v_writelane_b32 v252, s9, 42
	s_add_u32 s8, s30, 0x1b600000
	s_addc_u32 s9, s31, 0
	v_writelane_b32 v252, s8, 43
	v_mov_b32_e32 v200, 0x41b17218
	v_mov_b32_e32 v201, 0xff800000
	v_writelane_b32 v252, s9, 44
	s_add_u32 s8, s30, 0x1b700000
	s_addc_u32 s9, s31, 0
	v_writelane_b32 v252, s8, 45
	s_movk_i32 s34, 0x1000
	s_movk_i32 s35, 0x3a00
	v_writelane_b32 v252, s9, 46
	s_add_u32 s8, s30, 0x1b780000
	s_addc_u32 s9, s31, 0
	s_add_u32 s33, s30, 0x1b800000
	v_writelane_b32 v252, s8, 47
	s_addc_u32 s84, s31, 0
	s_mov_b32 s82, 0xbfb8aa3b
	v_writelane_b32 v252, s9, 48
	s_add_u32 s8, s30, 0x1dc00000
	s_addc_u32 s9, s31, 0
	v_writelane_b32 v252, s8, 49
	s_add_u32 s80, s30, 0x1ee00000
	s_addc_u32 s81, s31, 0
	v_writelane_b32 v252, s9, 50
	s_mov_b32 s83, 0x7f800000
	v_readlane_b32 s14, v252, 0
	s_cmpk_lt_i32 s14, 0x3c0
	s_cselect_b64 s[8:9], -1, 0
	v_writelane_b32 v252, s8, 51
	s_ashr_i32 s11, s3, 31
	s_mov_b32 s53, 0x2aaaaaab
	v_writelane_b32 v252, s9, 52
	s_ashr_i32 s8, s14, 31
	v_writelane_b32 v252, s8, 53
	s_lshr_b32 s8, s8, 29
	s_add_i32 s8, s14, s8
	s_ashr_i32 s9, s8, 3
	s_and_b32 s8, s8, -8
	s_sub_i32 s8, s14, s8
	s_add_u32 s18, s30, 0x4200
	v_writelane_b32 v252, s11, 54
	s_addc_u32 s19, s31, 0
	v_writelane_b32 v252, s18, 55
	s_mov_b32 s85, 0x3f317217
	s_mov_b64 s[88:89], 0x80
	v_writelane_b32 v252, s19, 56
	s_add_u32 s18, s30, 0x4400
	s_addc_u32 s19, s31, 0
	v_writelane_b32 v252, s18, 57
	s_mov_b64 s[90:91], 0x120000
	s_mov_b64 s[92:93], 0x240000
	v_writelane_b32 v252, s19, 58
	s_add_u32 s18, s30, 0x4500
	s_addc_u32 s19, s31, 0
	v_writelane_b32 v252, s18, 59
	s_mov_b32 s62, s15
	s_nop 0
	v_writelane_b32 v252, s19, 60
	s_add_u32 s18, s30, 0x4600
	s_addc_u32 s19, s31, 0
	v_writelane_b32 v252, s18, 61
	s_nop 1
	v_writelane_b32 v252, s19, 62
	s_add_u32 s18, s30, 0x4700
	s_addc_u32 s19, s31, 0
	v_writelane_b32 v252, s18, 63
	s_nop 0
	v_readlane_b32 s36, v252, 11
	v_writelane_b32 v253, s19, 0
	s_add_u32 s18, s30, 0x4800
	s_addc_u32 s19, s31, 0
	v_writelane_b32 v253, s18, 1
	v_readlane_b32 s42, v252, 17
	v_readlane_b32 s43, v252, 18
	v_writelane_b32 v253, s19, 2
	s_add_u32 s18, s30, 0x4900
	s_addc_u32 s19, s31, 0
	v_writelane_b32 v253, s18, 3
	v_readlane_b32 s44, v252, 19
	v_readlane_b32 s45, v252, 20
	v_writelane_b32 v253, s19, 4
	s_add_u32 s18, s30, 0x4a00
	s_addc_u32 s19, s31, 0
	v_writelane_b32 v253, s18, 5
	v_readlane_b32 s46, v252, 21
	v_readlane_b32 s47, v252, 22
	v_writelane_b32 v253, s19, 6
	s_add_u32 s18, s30, 0x4b00
	s_addc_u32 s19, s31, 0
	v_writelane_b32 v253, s18, 7
	v_readlane_b32 s48, v252, 23
	v_readlane_b32 s49, v252, 24
	v_writelane_b32 v253, s19, 8
	s_add_u32 s18, s30, 0x4c00
	s_addc_u32 s19, s31, 0
	v_writelane_b32 v253, s18, 9
	s_mov_b64 s[94:95], s[48:49]
	s_mov_b64 s[96:97], s[46:47]
	v_writelane_b32 v253, s19, 10
	s_add_u32 s18, s30, 0x4d00
	s_addc_u32 s19, s31, 0
	v_writelane_b32 v253, s18, 11
	v_readlane_b32 s37, v252, 12
	v_readlane_b32 s38, v252, 13
	v_writelane_b32 v253, s19, 12
	s_add_u32 s18, s30, 0x4e00
	s_addc_u32 s19, s31, 0
	v_writelane_b32 v253, s18, 13
	v_readlane_b32 s39, v252, 14
	v_readlane_b32 s40, v252, 15
	v_writelane_b32 v253, s19, 14
	s_add_u32 s18, s30, 0x4f00
	s_addc_u32 s19, s31, 0
	v_writelane_b32 v253, s18, 15
	v_readlane_b32 s41, v252, 16
	v_readlane_b32 s50, v252, 25
	v_writelane_b32 v253, s19, 16
	s_add_u32 s18, s30, 0x5000
	s_addc_u32 s19, s31, 0
	v_writelane_b32 v253, s18, 17
	v_readlane_b32 s51, v252, 26
	s_nop 0
	v_writelane_b32 v253, s19, 18
	s_add_u32 s18, s30, 0x5100
	s_addc_u32 s19, s31, 0
	v_writelane_b32 v253, s18, 19
	s_nop 1
	v_writelane_b32 v253, s19, 20
	s_add_u32 s18, s30, 0x5200
	s_addc_u32 s19, s31, 0
	v_writelane_b32 v253, s18, 21
	s_nop 1
	v_writelane_b32 v253, s19, 22
	s_add_u32 s18, s30, 0x5300
	s_addc_u32 s19, s31, 0
	v_writelane_b32 v253, s18, 23
	s_cmp_eq_u32 s2, 15
	s_nop 0
	v_writelane_b32 v253, s19, 24
	s_cselect_b64 s[18:19], -1, 0
	v_writelane_b32 v253, s18, 25
	s_cmp_eq_u32 s2, 14
	s_nop 0
	v_writelane_b32 v253, s19, 26
	s_cselect_b64 s[18:19], -1, 0
	v_writelane_b32 v253, s18, 27
	s_cmp_eq_u32 s2, 13
	s_nop 0
	v_writelane_b32 v253, s19, 28
	s_cselect_b64 s[18:19], -1, 0
	v_writelane_b32 v253, s18, 29
	s_cmp_eq_u32 s2, 12
	s_nop 0
	v_writelane_b32 v253, s19, 30
	s_cselect_b64 s[18:19], -1, 0
	v_writelane_b32 v253, s18, 31
	s_cmp_eq_u32 s2, 11
	s_nop 0
	v_writelane_b32 v253, s19, 32
	s_cselect_b64 s[18:19], -1, 0
	v_writelane_b32 v253, s18, 33
	s_cmp_eq_u32 s2, 10
	s_nop 0
	v_writelane_b32 v253, s19, 34
	s_cselect_b64 s[18:19], -1, 0
	v_writelane_b32 v253, s18, 35
	s_cmp_eq_u32 s2, 9
	s_nop 0
	v_writelane_b32 v253, s19, 36
	s_cselect_b64 s[18:19], -1, 0
	v_writelane_b32 v253, s18, 37
	s_cmp_eq_u32 s2, 8
	s_nop 0
	v_writelane_b32 v253, s19, 38
	s_cselect_b64 s[18:19], -1, 0
	v_writelane_b32 v253, s18, 39
	s_cmp_eq_u32 s2, 7
	s_nop 0
	v_writelane_b32 v253, s19, 40
	s_cselect_b64 s[18:19], -1, 0
	v_writelane_b32 v253, s18, 41
	s_cmp_eq_u32 s2, 6
	s_nop 0
	v_writelane_b32 v253, s19, 42
	s_cselect_b64 s[18:19], -1, 0
	v_writelane_b32 v253, s18, 43
	s_cmp_eq_u32 s2, 5
	s_nop 0
	v_writelane_b32 v253, s19, 44
	s_cselect_b64 s[18:19], -1, 0
	v_writelane_b32 v253, s18, 45
	s_cmp_eq_u32 s2, 4
	s_nop 0
	v_writelane_b32 v253, s19, 46
	s_cselect_b64 s[18:19], -1, 0
	v_writelane_b32 v253, s18, 47
	s_cmp_eq_u32 s2, 3
	s_nop 0
	v_writelane_b32 v253, s19, 48
	s_cselect_b64 s[18:19], -1, 0
	v_writelane_b32 v253, s18, 49
	s_cmp_eq_u32 s2, 2
	s_nop 0
	v_writelane_b32 v253, s19, 50
	s_cselect_b64 s[18:19], -1, 0
	v_writelane_b32 v253, s18, 51
	s_cmp_eq_u32 s2, 1
	s_nop 0
	v_writelane_b32 v253, s19, 52
	s_cselect_b64 s[18:19], -1, 0
	v_writelane_b32 v253, s18, 53
	s_cmp_eq_u32 s2, 0
	s_nop 0
	v_writelane_b32 v253, s19, 54
	s_cselect_b64 s[18:19], -1, 0
	s_lshl_b32 s2, s10, 2
	s_add_u32 s2, s4, s2
	s_addc_u32 s4, s5, 0
	v_writelane_b32 v253, s18, 55
	s_add_u32 s10, s2, 0x1400
	s_addc_u32 s11, s4, 0
	v_writelane_b32 v253, s19, 56
	v_writelane_b32 v253, s10, 57
	s_nop 1
	v_writelane_b32 v253, s11, 58
	s_add_u32 s10, s2, 0x2400
	s_addc_u32 s11, s4, 0
	v_writelane_b32 v253, s10, 59
	s_add_u32 s4, s30, 0x7400
	s_addc_u32 s5, s31, 0
	v_writelane_b32 v253, s11, 60
	v_writelane_b32 v253, s4, 61
	s_nop 1
	v_writelane_b32 v253, s5, 62
	s_add_u32 s4, s30, 0x7500
	s_addc_u32 s5, s31, 0
	s_lshl_b32 s18, s14, 3
	s_lshl_b32 s20, s3, 3
	v_writelane_b32 v253, s4, 63
	s_cmpk_lt_i32 s14, 0x200
	s_nop 0
	v_writelane_b32 v254, s5, 0
	s_cselect_b64 s[4:5], -1, 0
	v_writelane_b32 v254, s4, 1
	s_cmp_eq_u32 s14, 0
	s_nop 0
	v_writelane_b32 v254, s5, 2
	s_cselect_b64 s[4:5], -1, 0
	s_add_u32 s98, s30, 0x1ee30000
	s_addc_u32 s99, s31, 0
	v_writelane_b32 v254, s4, 3
	s_cmpk_lt_i32 s14, 0x100
	s_nop 0
	v_writelane_b32 v254, s5, 4
	s_cselect_b64 s[4:5], -1, 0
	v_writelane_b32 v254, s4, 5
	s_lshl_b32 s2, s3, 9
	s_nop 0
	v_writelane_b32 v254, s5, 6
	v_writelane_b32 v254, s2, 7
	s_lshl_b32 s2, s14, 9
	v_writelane_b32 v254, s2, 8
	s_lshl_b32 s2, s3, 10
	v_writelane_b32 v254, s2, 9
	s_lshl_b32 s2, s8, 5
	s_cmp_lt_i32 s8, 0
	s_movk_i32 s4, 0x79
	s_cselect_b32 s4, s4, 0x78
	s_mul_i32 s4, s8, s4
	s_mul_i32 s8, s8, 33
	s_cselect_b32 s2, s8, s2
	s_add_i32 s4, s4, s9
	s_mul_hi_i32 s5, s4, 0x88888889
	s_add_i32 s5, s5, s4
	s_lshr_b32 s8, s5, 31
	s_ashr_i32 s5, s5, 7
	s_add_i32 s5, s5, s8
	s_mul_i32 s8, s5, 0xf0
	s_sub_i32 s4, s4, s8
	s_add_i32 s2, s2, s9
	s_bfe_u32 s8, s4, 0x3001c
	s_ashr_i32 s9, s2, 31
	s_add_i32 s8, s4, s8
	s_lshr_b32 s9, s9, 26
	s_and_b32 s10, s8, 0xfff8
	s_add_i32 s9, s2, s9
	s_sub_i32 s4, s4, s10
	s_and_b32 s10, s9, 0xffc0
	s_sub_i32 s2, s2, s10
	s_bfe_i32 s10, s2, 0x80000
	s_bfe_u32 s10, s10, 0x3000c
	s_add_i32 s10, s2, s10
	s_and_b32 s11, s10, 0xf8
	s_lshl_b32 s5, s5, 3
	s_sext_i32_i16 s4, s4
	s_sub_i32 s2, s2, s11
	s_add_i32 s22, s5, s4
	s_ashr_i32 s4, s9, 6
	s_sext_i32_i16 s8, s8
	s_lshl_b32 s4, s4, 3
	s_sext_i32_i8 s2, s2
	s_bfe_i32 s5, s10, 0x80000
	s_add_i32 s10, s4, s2
	s_ashr_i32 s2, s8, 3
	v_writelane_b32 v254, s2, 10
	s_lshr_b32 s2, s8, 3
	s_sext_i32_i16 s9, s5
	s_bfe_i64 s[4:5], s[2:3], 0x100000
	s_lshl_b64 s[4:5], s[4:5], 20
	v_writelane_b32 v254, s4, 11
	s_ashr_i32 s2, s9, 3
	s_ashr_i32 s23, s22, 31
	v_writelane_b32 v254, s5, 12
	v_writelane_b32 v254, s2, 13
	s_mov_b32 s4, s22
	v_writelane_b32 v254, s4, 14
	s_lshr_b32 s2, s9, 3
	s_nop 0
	v_writelane_b32 v254, s5, 15
	s_lshl_b64 s[4:5], s[22:23], 20
	s_add_u32 s4, s16, s4
	s_addc_u32 s5, s17, s5
	s_add_u32 s8, s4, 0x80000
	v_writelane_b32 v254, s4, 16
	s_addc_u32 s9, s5, 0
	s_ashr_i32 s11, s10, 31
	v_writelane_b32 v254, s5, 17
	v_writelane_b32 v254, s8, 18
	s_bfe_i64 s[4:5], s[2:3], 0x100000
	s_lshl_b64 s[4:5], s[4:5], 20
	v_writelane_b32 v254, s9, 19
	v_writelane_b32 v254, s4, 20
	s_mov_b32 s2, s10
	s_movk_i32 s22, 0x2000
	v_writelane_b32 v254, s5, 21
	v_writelane_b32 v254, s2, 22
	s_lshl_b64 s[4:5], s[10:11], 20
	s_add_u32 s4, s12, s4
	v_writelane_b32 v254, s3, 23
	s_mul_i32 s2, s7, s6
	s_mul_i32 s2, s2, s3
	s_addc_u32 s5, s13, s5
	v_writelane_b32 v254, s2, 24
	s_add_u32 s6, s4, 0x80000
	v_writelane_b32 v254, s4, 25
	s_addc_u32 s7, s5, 0
	s_ashr_i32 s2, s18, 31
	v_writelane_b32 v254, s5, 26
	v_writelane_b32 v254, s6, 27
	s_add_i32 s4, 0, 0x20100
	s_ashr_i32 s21, s20, 31
	v_writelane_b32 v254, s7, 28
	v_writelane_b32 v254, s18, 29
	v_writelane_b32 v254, s2, 30
	s_lshl_b32 s2, s14, 7
	v_writelane_b32 v254, s2, 31
	s_lshl_b32 s2, s3, 7
	v_writelane_b32 v254, s2, 32
	s_lshl_b32 s2, s14, 5
	v_writelane_b32 v254, s2, 33
	s_lshl_b32 s2, s3, 5
	v_writelane_b32 v254, s2, 34
	s_lshl_b32 s2, s14, 1
	v_writelane_b32 v254, s2, 35
	s_lshl_b32 s2, s3, 1
	v_writelane_b32 v254, s2, 36
	s_add_i32 s2, 0, 0x20400
	v_writelane_b32 v254, s2, 37
	v_writelane_b32 v254, s4, 38
	s_add_i32 s4, 0, 0x20104
	v_writelane_b32 v254, s4, 39
	s_add_i32 s4, 0, 0x4d80
	v_writelane_b32 v254, s4, 40
	s_add_i32 s4, 0, 0x21000
	v_writelane_b32 v254, s4, 41
	s_add_i32 s4, 0, 0x21004
	v_writelane_b32 v254, s4, 42
	s_add_i32 s4, 0, 0x20404
	v_writelane_b32 v254, s4, 43
	s_add_i32 s4, 0, 0x15000
	v_writelane_b32 v254, s4, 44
	s_mov_b32 s4, s20
	v_writelane_b32 v254, s4, 45
	s_movk_i32 s23, 0xc0
	s_mov_b32 s2, 0x800000
	v_writelane_b32 v254, s5, 46
	s_lshl_b64 s[4:5], s[20:21], 2
	v_writelane_b32 v254, s4, 47
	s_mov_b64 s[18:19], s[44:45]
	s_mov_b64 s[20:21], s[42:43]
	v_writelane_b32 v254, s5, 48
	s_mov_b32 s62, -1
	s_sub_u32 s20, s20, 0x100
	s_subb_u32 s21, s21, 0
	s_sub_u32 s18, s18, 0x100
	s_subb_u32 s19, s19, 0
	s_sub_u32 s96, s96, 0x100
	s_subb_u32 s97, s97, 0
	s_sub_u32 s94, s94, 0x100
	s_subb_u32 s95, s95, 0
	s_branch .Lbar5_entry

.Lbar5_entry:
	s_waitcnt vmcnt(0)
	s_barrier
	s_mov_b64 s[4:5], exec
	v_readlane_b32 s6, v252, 31
	v_readlane_b32 s7, v252, 32
	s_and_b64 s[6:7], s[4:5], s[6:7]
	s_mov_b64 exec, s[6:7]
	s_cbranch_execz .LBB0_113
	v_readlane_b32 s6, v254, 38
	s_waitcnt vmcnt(0) expcnt(0) lgkmcnt(0)
	s_nop 0
	v_mov_b32_e32 v0, s6
	ds_read_b32 v3, v0
	v_readlane_b32 s6, v254, 39
	s_waitcnt lgkmcnt(0)
	v_cmp_ne_u32_e32 vcc, 0, v3
	v_mov_b32_e32 v0, s6
	ds_read_b32 v2, v0
	s_cbranch_vccnz .LBB0_682
	s_mov_b32 s14, 1
	s_branch .LBB0_670

.LBB0_670:
	v_readlane_b32 s6, v252, 57
	v_readlane_b32 s7, v252, 58
	v_readlane_b32 s8, v254, 24
	s_waitcnt lgkmcnt(0)
	s_mov_b64 s[10:11], exec
	s_mov_b64 exec, 0xffff
	v_mbcnt_lo_u32_b32 v18, -1, 0
	v_lshlrev_b32_e32 v18, 8, v18
	s_nop 1
	global_load_dword v19, v18, s[6:7] sc1
	s_waitcnt vmcnt(0)
	s_mov_b64 exec, s[10:11]
	s_nop 0
	v_readlane_b32 s6, v19, 0
	v_readlane_b32 s7, v19, 1
	v_readlane_b32 s9, v19, 2
	v_readlane_b32 s10, v19, 3
	v_mov_b32_e32 v0, s6
	v_mov_b32_e32 v2, s7
	v_mov_b32_e32 v3, s9
	v_mov_b32_e32 v4, s10
	v_readlane_b32 s6, v19, 4
	v_readlane_b32 s7, v19, 5
	v_readlane_b32 s9, v19, 6
	v_readlane_b32 s10, v19, 7
	v_mov_b32_e32 v5, s6
	v_mov_b32_e32 v6, s7
	v_mov_b32_e32 v7, s9
	v_mov_b32_e32 v8, s10
	v_readlane_b32 s6, v19, 8
	v_readlane_b32 s7, v19, 9
	v_readlane_b32 s9, v19, 10
	v_readlane_b32 s10, v19, 11
	v_mov_b32_e32 v9, s6
	v_mov_b32_e32 v10, s7
	v_mov_b32_e32 v11, s9
	v_mov_b32_e32 v12, s10
	v_readlane_b32 s6, v19, 12
	v_readlane_b32 s7, v19, 13
	v_readlane_b32 s9, v19, 14
	v_readlane_b32 s10, v19, 15
	v_mov_b32_e32 v13, s6
	v_mov_b32_e32 v14, s7
	v_mov_b32_e32 v15, s9
	v_mov_b32_e32 v16, s10
	v_add3_u32 v17, v0, v2, v3
	v_add3_u32 v17, v17, v4, v5
	v_add3_u32 v17, v17, v6, v7
	v_add3_u32 v17, v17, v8, v9
	v_add3_u32 v17, v17, v10, v11
	v_add3_u32 v17, v17, v12, v13
	v_add3_u32 v17, v17, v14, v15
	v_add_u32_e32 v17, v17, v16
	s_mov_b64 s[6:7], -1
	v_cmp_eq_u32_e32 vcc, s8, v17
	s_mov_b64 s[8:9], -1
	s_cbranch_vccnz .LBB0_669
	s_and_b32 s6, s14, 0xff
	s_cmp_eq_u32 s6, 0
	s_mov_b64 s[6:7], -1
	s_mov_b64 s[10:11], -1
	s_sleep 1
	s_cbranch_scc0 .LBB0_674
	v_readlane_b32 s6, v252, 55
	v_readlane_b32 s7, v252, 56
	s_nop 4
	global_load_dword v17, v1, s[6:7] sc1
	s_waitcnt vmcnt(0)
	v_cmp_eq_u32_e32 vcc, 0, v17
	s_cbranch_vccnz .LBB0_676
	s_mov_b64 s[10:11], 0
	s_mov_b64 s[6:7], -1
